# comb2 + J2: PV step head - flag read, first V fragment group and P fragments issued together; flag test overlaps their latency; rescale path reads alpha in two halves
# baseline (speedup 1.0000x reference)
; __device__ __forceinline__ int crow(int r, int hi) { return (r & 3) + 8 * (r >> 2) + 4 * hi; }
; __device__ __forceinline__ void attn2_block(const Blk& c, char* lds) {
;     ...
;             if (s >= 1) {
;                 const int par = (s - 1) & 1;
;                 const unsigned fl = (unsigned)__builtin_amdgcn_readfirstlane((int)FLb[par]);
;                 if (fl) {
; #pragma unroll
;                     for (int r = 0; r < 16; ++r) { const float a = ALb[par * 32 + att::crow(r, hi)];
; #pragma unroll
;                         for (int d_ = 0; d_ < 8; ++d_) o[d_][r] *= a; } }
;                 const char* pr = Pb + par * 4096 + lane * 16;
;                 const bf16x8 pa0 = *(const bf16x8*)(pr), pa1 = *(const bf16x8*)(pr + 1024), pa2 = *(const bf16x8*)(pr + 2048), pa3 = *(const bf16x8*)(pr + 3072);
.LBB0_546:
	s_andn2_b32 s85, 1, s85
	s_lshl_b32 s10, s85, 2
	s_add_i32 s10, s79, s10
	v_mov_b32_e32 v2, s10
	ds_read_b32 v177, v2
	v_lshl_add_u32 v176, s85, 15, v231
	ds_read_b64_tr_b16 v[232:233], v176 offset:0
	ds_read_b64_tr_b16 v[234:235], v176 offset:2048
	ds_read_b64_tr_b16 v[242:243], v176 offset:4096
	ds_read_b64_tr_b16 v[244:245], v176 offset:6144
	ds_read_b64_tr_b16 v[246:247], v176 offset:8192
	ds_read_b64_tr_b16 v[248:249], v176 offset:10240
	ds_read_b64_tr_b16 v[250:251], v176 offset:12288
	ds_read_b64_tr_b16 v[252:253], v176 offset:14336
	v_lshl_add_u32 v2, s85, 12, v230
	ds_read_b128 v[192:195], v2
	ds_read_b128 v[188:191], v2 offset:1024
	ds_read_b128 v[184:187], v2 offset:2048
	ds_read_b128 v[180:183], v2 offset:3072
	s_waitcnt lgkmcnt(12)
	v_readfirstlane_b32 s10, v177
	s_cmp_eq_u32 s10, 0
	s_cbranch_scc1 .LBB0_548
	v_lshl_add_u32 v2, s85, 7, v212
	ds_read_b128 v[156:159], v2
	ds_read_b128 v[160:163], v2 offset:32
	s_waitcnt lgkmcnt(0)
	v_pk_mul_f32 v[122:123], v[122:123], v[162:163]
	v_pk_mul_f32 v[118:119], v[118:119], v[158:159]
	v_pk_mul_f32 v[120:121], v[120:121], v[160:161]
	v_pk_mul_f32 v[116:117], v[116:117], v[156:157]
	v_pk_mul_f32 v[106:107], v[106:107], v[162:163]
	v_pk_mul_f32 v[102:103], v[102:103], v[158:159]
	v_pk_mul_f32 v[104:105], v[104:105], v[160:161]
	v_pk_mul_f32 v[100:101], v[100:101], v[156:157]
	v_pk_mul_f32 v[90:91], v[90:91], v[162:163]
	v_pk_mul_f32 v[86:87], v[86:87], v[158:159]
	v_pk_mul_f32 v[88:89], v[88:89], v[160:161]
	v_pk_mul_f32 v[84:85], v[84:85], v[156:157]
	v_pk_mul_f32 v[74:75], v[74:75], v[162:163]
	v_pk_mul_f32 v[70:71], v[70:71], v[158:159]
	v_pk_mul_f32 v[72:73], v[72:73], v[160:161]
	v_pk_mul_f32 v[68:69], v[68:69], v[156:157]
	v_pk_mul_f32 v[58:59], v[58:59], v[162:163]
	v_pk_mul_f32 v[54:55], v[54:55], v[158:159]
	v_pk_mul_f32 v[56:57], v[56:57], v[160:161]
	v_pk_mul_f32 v[52:53], v[52:53], v[156:157]
	v_pk_mul_f32 v[42:43], v[42:43], v[162:163]
	v_pk_mul_f32 v[38:39], v[38:39], v[158:159]
	v_pk_mul_f32 v[40:41], v[40:41], v[160:161]
	v_pk_mul_f32 v[36:37], v[36:37], v[156:157]
	v_pk_mul_f32 v[26:27], v[26:27], v[162:163]
	v_pk_mul_f32 v[22:23], v[22:23], v[158:159]
	v_pk_mul_f32 v[24:25], v[24:25], v[160:161]
	v_pk_mul_f32 v[20:21], v[20:21], v[156:157]
	v_pk_mul_f32 v[10:11], v[10:11], v[162:163]
	v_pk_mul_f32 v[6:7], v[6:7], v[158:159]
	v_pk_mul_f32 v[8:9], v[8:9], v[160:161]
	v_pk_mul_f32 v[4:5], v[4:5], v[156:157]
	ds_read_b128 v[156:159], v2 offset:64
	ds_read_b128 v[160:163], v2 offset:96
	s_waitcnt lgkmcnt(0)
	v_pk_mul_f32 v[130:131], v[130:131], v[162:163]
	v_pk_mul_f32 v[126:127], v[126:127], v[158:159]
	v_pk_mul_f32 v[128:129], v[128:129], v[160:161]
	v_pk_mul_f32 v[124:125], v[124:125], v[156:157]
	v_pk_mul_f32 v[114:115], v[114:115], v[162:163]
	v_pk_mul_f32 v[110:111], v[110:111], v[158:159]
	v_pk_mul_f32 v[112:113], v[112:113], v[160:161]
	v_pk_mul_f32 v[108:109], v[108:109], v[156:157]
	v_pk_mul_f32 v[98:99], v[98:99], v[162:163]
	v_pk_mul_f32 v[94:95], v[94:95], v[158:159]
	v_pk_mul_f32 v[96:97], v[96:97], v[160:161]
	v_pk_mul_f32 v[92:93], v[92:93], v[156:157]
	v_pk_mul_f32 v[82:83], v[82:83], v[162:163]
	v_pk_mul_f32 v[78:79], v[78:79], v[158:159]
	v_pk_mul_f32 v[80:81], v[80:81], v[160:161]
	v_pk_mul_f32 v[76:77], v[76:77], v[156:157]
	v_pk_mul_f32 v[66:67], v[66:67], v[162:163]
	v_pk_mul_f32 v[62:63], v[62:63], v[158:159]
	v_pk_mul_f32 v[64:65], v[64:65], v[160:161]
	v_pk_mul_f32 v[60:61], v[60:61], v[156:157]
	v_pk_mul_f32 v[50:51], v[50:51], v[162:163]
	v_pk_mul_f32 v[46:47], v[46:47], v[158:159]
	v_pk_mul_f32 v[48:49], v[48:49], v[160:161]
	v_pk_mul_f32 v[44:45], v[44:45], v[156:157]
	v_pk_mul_f32 v[34:35], v[34:35], v[162:163]
	v_pk_mul_f32 v[30:31], v[30:31], v[158:159]
	v_pk_mul_f32 v[32:33], v[32:33], v[160:161]
	v_pk_mul_f32 v[28:29], v[28:29], v[156:157]
	v_pk_mul_f32 v[18:19], v[18:19], v[162:163]
	v_pk_mul_f32 v[14:15], v[14:15], v[158:159]
	v_pk_mul_f32 v[16:17], v[16:17], v[160:161]
	v_pk_mul_f32 v[12:13], v[12:13], v[156:157]
; template <int VB>
; __device__ __forceinline__ void pv_tile(f32x16* o, int vb0, bf16x8 pa0, bf16x8 pa1, bf16x8 pa2, bf16x8 pa3) {
;     ...
;     PV_D0(0); PV_D0(1); PV_D0(2); PV_D0(3);
; __device__ __forceinline__ void attn2_block(const Blk& c, char* lds) {
;     ...
;                 const char* pr = Pb + par * 4096 + lane * 16;
;                 const bf16x8 pa0 = *(const bf16x8*)(pr), pa1 = *(const bf16x8*)(pr + 1024), pa2 = *(const bf16x8*)(pr + 2048), pa3 = *(const bf16x8*)(pr + 3072);
;                 const int vb = vbase + par * 2 * SHM_V;
;                 att::pv_tile<0>(o, vb, pa0, pa1, pa2, pa3);
;                 att::pv_tile<0>(o + 4, vb + SHM_V, pa0, pa1, pa2, pa3);
;             }
;             __syncthreads();
.LBB0_548:
	v_lshl_add_u32 v2, s85, 15, v231
	s_waitcnt lgkmcnt(3)
	s_waitcnt lgkmcnt(3)
	v_mfma_f32_32x32x16_bf16 v[116:131], v[192:195], v[232:235], v[116:131]
	ds_read_b64_tr_b16 v[232:233], v2 offset:0x200
	ds_read_b64_tr_b16 v[234:235], v2 offset:0xa00
	s_waitcnt lgkmcnt(4)
	v_mfma_f32_32x32x16_bf16 v[116:131], v[188:191], v[242:245], v[116:131]
	ds_read_b64_tr_b16 v[242:243], v2 offset:0x1200
	ds_read_b64_tr_b16 v[244:245], v2 offset:0x1a00
	s_waitcnt lgkmcnt(5)
	v_mfma_f32_32x32x16_bf16 v[116:131], v[184:187], v[246:249], v[116:131]
	ds_read_b64_tr_b16 v[246:247], v2 offset:0x2200
	ds_read_b64_tr_b16 v[248:249], v2 offset:0x2a00
	s_waitcnt lgkmcnt(6)
	v_mfma_f32_32x32x16_bf16 v[116:131], v[180:183], v[250:253], v[116:131]
	ds_read_b64_tr_b16 v[250:251], v2 offset:0x3200
	ds_read_b64_tr_b16 v[252:253], v2 offset:0x3a00
	s_waitcnt lgkmcnt(6)
	v_mfma_f32_32x32x16_bf16 v[100:115], v[192:195], v[232:235], v[100:115]
	ds_read_b64_tr_b16 v[232:233], v2 offset:0x400
	ds_read_b64_tr_b16 v[234:235], v2 offset:0xc00
	s_waitcnt lgkmcnt(6)
	v_mfma_f32_32x32x16_bf16 v[100:115], v[188:191], v[242:245], v[100:115]
	ds_read_b64_tr_b16 v[242:243], v2 offset:0x1400
	ds_read_b64_tr_b16 v[244:245], v2 offset:0x1c00
	s_waitcnt lgkmcnt(6)
	v_mfma_f32_32x32x16_bf16 v[100:115], v[184:187], v[246:249], v[100:115]
	ds_read_b64_tr_b16 v[246:247], v2 offset:0x2400
	ds_read_b64_tr_b16 v[248:249], v2 offset:0x2c00
	s_waitcnt lgkmcnt(6)
	v_mfma_f32_32x32x16_bf16 v[100:115], v[180:183], v[250:253], v[100:115]
	ds_read_b64_tr_b16 v[250:251], v2 offset:0x3400
	ds_read_b64_tr_b16 v[252:253], v2 offset:0x3c00
	s_waitcnt lgkmcnt(6)
	v_mfma_f32_32x32x16_bf16 v[84:99], v[192:195], v[232:235], v[84:99]
	ds_read_b64_tr_b16 v[232:233], v2 offset:0x600
	ds_read_b64_tr_b16 v[234:235], v2 offset:0xe00
	s_waitcnt lgkmcnt(6)
	v_mfma_f32_32x32x16_bf16 v[84:99], v[188:191], v[242:245], v[84:99]
	ds_read_b64_tr_b16 v[242:243], v2 offset:0x1600
	ds_read_b64_tr_b16 v[244:245], v2 offset:0x1e00
	s_waitcnt lgkmcnt(6)
	v_mfma_f32_32x32x16_bf16 v[84:99], v[184:187], v[246:249], v[84:99]
	ds_read_b64_tr_b16 v[246:247], v2 offset:0x2600
	ds_read_b64_tr_b16 v[248:249], v2 offset:0x2e00
	s_waitcnt lgkmcnt(6)
	v_mfma_f32_32x32x16_bf16 v[84:99], v[180:183], v[250:253], v[84:99]
	ds_read_b64_tr_b16 v[250:251], v2 offset:0x3600
	ds_read_b64_tr_b16 v[252:253], v2 offset:0x3e00
	s_waitcnt lgkmcnt(6)
	v_mfma_f32_32x32x16_bf16 v[68:83], v[192:195], v[232:235], v[68:83]
	v_add_u32_e32 v2, 0x4000, v2
	ds_read_b64_tr_b16 v[232:233], v2 offset:0
	ds_read_b64_tr_b16 v[234:235], v2 offset:0x800
	s_waitcnt lgkmcnt(6)
	v_mfma_f32_32x32x16_bf16 v[68:83], v[188:191], v[242:245], v[68:83]
	ds_read_b64_tr_b16 v[242:243], v2 offset:0x1000
	ds_read_b64_tr_b16 v[244:245], v2 offset:0x1800
	s_waitcnt lgkmcnt(6)
	v_mfma_f32_32x32x16_bf16 v[68:83], v[184:187], v[246:249], v[68:83]
	ds_read_b64_tr_b16 v[246:247], v2 offset:0x2000
	ds_read_b64_tr_b16 v[248:249], v2 offset:0x2800
	s_waitcnt lgkmcnt(6)
	v_mfma_f32_32x32x16_bf16 v[68:83], v[180:183], v[250:253], v[68:83]
	ds_read_b64_tr_b16 v[250:251], v2 offset:0x3000
	ds_read_b64_tr_b16 v[252:253], v2 offset:0x3800
	s_waitcnt lgkmcnt(6)
	v_mfma_f32_32x32x16_bf16 v[52:67], v[192:195], v[232:235], v[52:67]
	ds_read_b64_tr_b16 v[232:233], v2 offset:0x200
	ds_read_b64_tr_b16 v[234:235], v2 offset:0xa00
	s_waitcnt lgkmcnt(6)
	v_mfma_f32_32x32x16_bf16 v[52:67], v[188:191], v[242:245], v[52:67]
	ds_read_b64_tr_b16 v[242:243], v2 offset:0x1200
	ds_read_b64_tr_b16 v[244:245], v2 offset:0x1a00
	s_waitcnt lgkmcnt(6)
	v_mfma_f32_32x32x16_bf16 v[52:67], v[184:187], v[246:249], v[52:67]
	ds_read_b64_tr_b16 v[246:247], v2 offset:0x2200
	ds_read_b64_tr_b16 v[248:249], v2 offset:0x2a00
	s_waitcnt lgkmcnt(6)
	v_mfma_f32_32x32x16_bf16 v[52:67], v[180:183], v[250:253], v[52:67]
	ds_read_b64_tr_b16 v[250:251], v2 offset:0x3200
	ds_read_b64_tr_b16 v[252:253], v2 offset:0x3a00
	s_waitcnt lgkmcnt(6)
	v_mfma_f32_32x32x16_bf16 v[36:51], v[192:195], v[232:235], v[36:51]
	ds_read_b64_tr_b16 v[232:233], v2 offset:0x400
	ds_read_b64_tr_b16 v[234:235], v2 offset:0xc00
	s_waitcnt lgkmcnt(6)
	v_mfma_f32_32x32x16_bf16 v[36:51], v[188:191], v[242:245], v[36:51]
	ds_read_b64_tr_b16 v[242:243], v2 offset:0x1400
	ds_read_b64_tr_b16 v[244:245], v2 offset:0x1c00
	s_waitcnt lgkmcnt(6)
	v_mfma_f32_32x32x16_bf16 v[36:51], v[184:187], v[246:249], v[36:51]
	ds_read_b64_tr_b16 v[246:247], v2 offset:0x2400
	ds_read_b64_tr_b16 v[248:249], v2 offset:0x2c00
	s_waitcnt lgkmcnt(6)
	v_mfma_f32_32x32x16_bf16 v[36:51], v[180:183], v[250:253], v[36:51]
	ds_read_b64_tr_b16 v[250:251], v2 offset:0x3400
	ds_read_b64_tr_b16 v[252:253], v2 offset:0x3c00
	s_waitcnt lgkmcnt(6)
	v_mfma_f32_32x32x16_bf16 v[20:35], v[192:195], v[232:235], v[20:35]
	ds_read_b64_tr_b16 v[232:233], v2 offset:0x600
	ds_read_b64_tr_b16 v[234:235], v2 offset:0xe00
	s_waitcnt lgkmcnt(6)
	v_mfma_f32_32x32x16_bf16 v[20:35], v[188:191], v[242:245], v[20:35]
	ds_read_b64_tr_b16 v[242:243], v2 offset:0x1600
	ds_read_b64_tr_b16 v[244:245], v2 offset:0x1e00
	s_waitcnt lgkmcnt(6)
	v_mfma_f32_32x32x16_bf16 v[20:35], v[184:187], v[246:249], v[20:35]
	ds_read_b64_tr_b16 v[246:247], v2 offset:0x2600
	ds_read_b64_tr_b16 v[248:249], v2 offset:0x2e00
	s_waitcnt lgkmcnt(6)
	v_mfma_f32_32x32x16_bf16 v[20:35], v[180:183], v[250:253], v[20:35]
	ds_read_b64_tr_b16 v[250:251], v2 offset:0x3600
	ds_read_b64_tr_b16 v[252:253], v2 offset:0x3e00
	s_waitcnt lgkmcnt(0)
	v_mfma_f32_32x32x16_bf16 v[4:19], v[192:195], v[232:235], v[4:19]
	s_waitcnt vmcnt(0)
	s_barrier
	v_mfma_f32_32x32x16_bf16 v[4:19], v[188:191], v[242:245], v[4:19]
	v_mfma_f32_32x32x16_bf16 v[4:19], v[184:187], v[246:249], v[4:19]
	v_mfma_f32_32x32x16_bf16 v[4:19], v[180:183], v[250:253], v[4:19]
	s_branch .LBB0_543
